# v34: v31 with the cache-panel conversion of XCD 7 in the last position (after all projection units) instead of sharing the first position with XCD 0
# speedup vs baseline: 1.0141x; 1.0014x over previous
.LBB0_434:
	s_cmp_lt_i32 s96, 4
	s_cselect_b64 s[4:5], -1, 0
	v_writelane_b32 v238, s87, 4
	s_and_b64 s[0:1], s[4:5], s[0:1]
	v_writelane_b32 v238, s96, 5
	s_andn2_b64 vcc, exec, s[0:1]
	s_nop 0
	v_writelane_b32 v238, s97, 6
	v_writelane_b32 v238, s84, 7
	s_cbranch_vccnz .LBB0_846
	s_and_b32 s0, s94, 7
	s_cmp_eq_u32 s0, 7
	s_cselect_b32 s44, 6, s0
	s_cmp_lt_i32 s44, 1
	s_cselect_b64 s[0:1], -1, 0
	s_cmpk_gt_i32 s94, 0x58a
	s_cselect_b64 s[2:3], -1, 0
	s_or_b64 s[2:3], s[2:3], s[0:1]
	s_and_b64 vcc, exec, s[2:3]
	s_cbranch_vccnz .LBB0_441
	s_ashr_i32 s0, s94, 31
	s_lshr_b32 s0, s0, 29
	s_add_i32 s6, s94, s0
	s_and_b32 s0, s6, -8
	s_sub_i32 s7, s94, s0
	s_cmp_gt_i32 s7, 2
	s_cbranch_scc0 .LBB0_438
	s_mul_i32 s0, s7, 0xb1
	s_add_i32 s8, s0, 3
	s_cbranch_execz .LBB0_439
	s_branch .LBB0_440
